# final RMSNorm loop hand-written: gains loaded once, rows software-pipelined (was four dependent round trips per row)
# speedup vs baseline: 1.0577x; 1.0013x over previous
.LBB0_2406:
	s_cmp_lt_i32 s50, 14
	s_cselect_b64 s[0:1], -1, 0
	s_and_b64 s[0:1], s[0:1], s[4:5]
	s_andn2_b64 vcc, exec, s[0:1]
	s_cbranch_vccnz .LBB0_2410
	s_add_i32 s0, 0, 0x20110
	v_mov_b32_e32 v0, s0
	s_waitcnt lgkmcnt(0)
	ds_read_b64 v[2:3], v0
	v_lshl_add_u32 v0, s2, 3, v179
	s_movk_i32 s0, 0x4400
	v_cmp_gt_i32_e32 vcc, s0, v0
	s_waitcnt lgkmcnt(0)
	v_readfirstlane_b32 s2, v2
	v_readfirstlane_b32 s3, v3
	s_and_saveexec_b64 s[0:1], vcc
	s_cbranch_execz .LBB0_2410
	v_and_b32_e32 v1, 63, v178
	v_lshlrev_b32_e32 v6, 4, v1
	v_mov_b32_e32 v7, 0
	s_nop 1
	global_load_dwordx4 v[24:27], v6, s[2:3] offset:0
	global_load_dwordx4 v[28:31], v6, s[2:3] offset:1024
	global_load_dwordx4 v[32:35], v6, s[2:3] offset:2048
	global_load_dwordx4 v[36:39], v6, s[2:3] offset:3072
	v_readfirstlane_b32 s9, v0
	s_lshl_b32 s10, s48, 3
	s_lshl_b32 s4, s9, 12
	s_add_u32 s12, s44, s4
	s_addc_u32 s13, s45, 0
	s_lshl_b32 s4, s9, 2
	s_add_u32 s4, s4, 0x55000
	s_add_u32 s14, s46, s4
	s_addc_u32 s15, s47, 0
	s_lshl_b32 s16, s10, 12
	s_lshl_b32 s17, s10, 2
	v_mov_b32_e32 v1, 0x3727c5ac
	s_mov_b32 s1, 0x800000
	global_load_dword v20, v7, s[14:15]
	global_load_dwordx4 v[40:43], v6, s[12:13] offset:0
	global_load_dwordx4 v[44:47], v6, s[12:13] offset:1024
	global_load_dwordx4 v[48:51], v6, s[12:13] offset:2048
	global_load_dwordx4 v[52:55], v6, s[12:13] offset:3072
.Lfn_a0:
	s_mov_b64 s[18:19], s[12:13]
	s_add_u32 s9, s9, s10
	s_add_u32 s12, s12, s16
	s_addc_u32 s13, s13, 0
	s_add_u32 s14, s14, s17
	s_addc_u32 s15, s15, 0
	s_cmp_gt_i32 s9, 0x43ff
	s_cbranch_scc1 .Lfn_a0_last
	global_load_dword v22, v7, s[14:15]
	global_load_dwordx4 v[56:59], v6, s[12:13] offset:0
	global_load_dwordx4 v[60:63], v6, s[12:13] offset:1024
	global_load_dwordx4 v[64:67], v6, s[12:13] offset:2048
	global_load_dwordx4 v[68:71], v6, s[12:13] offset:3072
	s_waitcnt vmcnt(5)
	v_fmamk_f32 v20, v20, 0x3a800000, v1
	v_mul_f32_e32 v21, 0x4b800000, v20
	v_cmp_gt_f32_e32 vcc, s1, v20
	s_nop 1
	v_cndmask_b32_e32 v20, v20, v21, vcc
	v_rsq_f32_e32 v20, v20
	s_nop 0
	v_mul_f32_e32 v21, 0x45800000, v20
	v_cndmask_b32_e32 v20, v20, v21, vcc
	v_pk_mul_f32 v[40:41], v[40:41], v[20:21] op_sel_hi:[1,0]
	v_pk_mul_f32 v[42:43], v[42:43], v[20:21] op_sel_hi:[1,0]
	v_pk_mul_f32 v[40:41], v[24:25], v[40:41]
	v_pk_mul_f32 v[42:43], v[26:27], v[42:43]
	global_store_dwordx4 v6, v[40:43], s[18:19] offset:0
	v_pk_mul_f32 v[44:45], v[44:45], v[20:21] op_sel_hi:[1,0]
	v_pk_mul_f32 v[46:47], v[46:47], v[20:21] op_sel_hi:[1,0]
	v_pk_mul_f32 v[44:45], v[28:29], v[44:45]
	v_pk_mul_f32 v[46:47], v[30:31], v[46:47]
	global_store_dwordx4 v6, v[44:47], s[18:19] offset:1024
	v_pk_mul_f32 v[48:49], v[48:49], v[20:21] op_sel_hi:[1,0]
	v_pk_mul_f32 v[50:51], v[50:51], v[20:21] op_sel_hi:[1,0]
	v_pk_mul_f32 v[48:49], v[32:33], v[48:49]
	v_pk_mul_f32 v[50:51], v[34:35], v[50:51]
	global_store_dwordx4 v6, v[48:51], s[18:19] offset:2048
	v_pk_mul_f32 v[52:53], v[52:53], v[20:21] op_sel_hi:[1,0]
	v_pk_mul_f32 v[54:55], v[54:55], v[20:21] op_sel_hi:[1,0]
	v_pk_mul_f32 v[52:53], v[36:37], v[52:53]
	v_pk_mul_f32 v[54:55], v[38:39], v[54:55]
	global_store_dwordx4 v6, v[52:55], s[18:19] offset:3072
.Lfn_loop:
.Lfn_b:
	s_mov_b64 s[18:19], s[12:13]
	s_add_u32 s9, s9, s10
	s_add_u32 s12, s12, s16
	s_addc_u32 s13, s13, 0
	s_add_u32 s14, s14, s17
	s_addc_u32 s15, s15, 0
	s_cmp_gt_i32 s9, 0x43ff
	s_cbranch_scc1 .Lfn_b_last
	global_load_dword v20, v7, s[14:15]
	global_load_dwordx4 v[40:43], v6, s[12:13] offset:0
	global_load_dwordx4 v[44:47], v6, s[12:13] offset:1024
	global_load_dwordx4 v[48:51], v6, s[12:13] offset:2048
	global_load_dwordx4 v[52:55], v6, s[12:13] offset:3072
	s_waitcnt vmcnt(9)
	v_fmamk_f32 v22, v22, 0x3a800000, v1
	v_mul_f32_e32 v23, 0x4b800000, v22
	v_cmp_gt_f32_e32 vcc, s1, v22
	s_nop 1
	v_cndmask_b32_e32 v22, v22, v23, vcc
	v_rsq_f32_e32 v22, v22
	s_nop 0
	v_mul_f32_e32 v23, 0x45800000, v22
	v_cndmask_b32_e32 v22, v22, v23, vcc
	v_pk_mul_f32 v[56:57], v[56:57], v[22:23] op_sel_hi:[1,0]
	v_pk_mul_f32 v[58:59], v[58:59], v[22:23] op_sel_hi:[1,0]
	v_pk_mul_f32 v[56:57], v[24:25], v[56:57]
	v_pk_mul_f32 v[58:59], v[26:27], v[58:59]
	global_store_dwordx4 v6, v[56:59], s[18:19] offset:0
	v_pk_mul_f32 v[60:61], v[60:61], v[22:23] op_sel_hi:[1,0]
	v_pk_mul_f32 v[62:63], v[62:63], v[22:23] op_sel_hi:[1,0]
	v_pk_mul_f32 v[60:61], v[28:29], v[60:61]
	v_pk_mul_f32 v[62:63], v[30:31], v[62:63]
	global_store_dwordx4 v6, v[60:63], s[18:19] offset:1024
	v_pk_mul_f32 v[64:65], v[64:65], v[22:23] op_sel_hi:[1,0]
	v_pk_mul_f32 v[66:67], v[66:67], v[22:23] op_sel_hi:[1,0]
	v_pk_mul_f32 v[64:65], v[32:33], v[64:65]
	v_pk_mul_f32 v[66:67], v[34:35], v[66:67]
	global_store_dwordx4 v6, v[64:67], s[18:19] offset:2048
	v_pk_mul_f32 v[68:69], v[68:69], v[22:23] op_sel_hi:[1,0]
	v_pk_mul_f32 v[70:71], v[70:71], v[22:23] op_sel_hi:[1,0]
	v_pk_mul_f32 v[68:69], v[36:37], v[68:69]
	v_pk_mul_f32 v[70:71], v[38:39], v[70:71]
	global_store_dwordx4 v6, v[68:71], s[18:19] offset:3072
.Lfn_a:
	s_mov_b64 s[18:19], s[12:13]
	s_add_u32 s9, s9, s10
	s_add_u32 s12, s12, s16
	s_addc_u32 s13, s13, 0
	s_add_u32 s14, s14, s17
	s_addc_u32 s15, s15, 0
	s_cmp_gt_i32 s9, 0x43ff
	s_cbranch_scc1 .Lfn_a_last
	global_load_dword v22, v7, s[14:15]
	global_load_dwordx4 v[56:59], v6, s[12:13] offset:0
	global_load_dwordx4 v[60:63], v6, s[12:13] offset:1024
	global_load_dwordx4 v[64:67], v6, s[12:13] offset:2048
	global_load_dwordx4 v[68:71], v6, s[12:13] offset:3072
	s_waitcnt vmcnt(9)
	v_fmamk_f32 v20, v20, 0x3a800000, v1
	v_mul_f32_e32 v21, 0x4b800000, v20
	v_cmp_gt_f32_e32 vcc, s1, v20
	s_nop 1
	v_cndmask_b32_e32 v20, v20, v21, vcc
	v_rsq_f32_e32 v20, v20
	s_nop 0
	v_mul_f32_e32 v21, 0x45800000, v20
	v_cndmask_b32_e32 v20, v20, v21, vcc
	v_pk_mul_f32 v[40:41], v[40:41], v[20:21] op_sel_hi:[1,0]
	v_pk_mul_f32 v[42:43], v[42:43], v[20:21] op_sel_hi:[1,0]
	v_pk_mul_f32 v[40:41], v[24:25], v[40:41]
	v_pk_mul_f32 v[42:43], v[26:27], v[42:43]
	global_store_dwordx4 v6, v[40:43], s[18:19] offset:0
	v_pk_mul_f32 v[44:45], v[44:45], v[20:21] op_sel_hi:[1,0]
	v_pk_mul_f32 v[46:47], v[46:47], v[20:21] op_sel_hi:[1,0]
	v_pk_mul_f32 v[44:45], v[28:29], v[44:45]
	v_pk_mul_f32 v[46:47], v[30:31], v[46:47]
	global_store_dwordx4 v6, v[44:47], s[18:19] offset:1024
	v_pk_mul_f32 v[48:49], v[48:49], v[20:21] op_sel_hi:[1,0]
	v_pk_mul_f32 v[50:51], v[50:51], v[20:21] op_sel_hi:[1,0]
	v_pk_mul_f32 v[48:49], v[32:33], v[48:49]
	v_pk_mul_f32 v[50:51], v[34:35], v[50:51]
	global_store_dwordx4 v6, v[48:51], s[18:19] offset:2048
	v_pk_mul_f32 v[52:53], v[52:53], v[20:21] op_sel_hi:[1,0]
	v_pk_mul_f32 v[54:55], v[54:55], v[20:21] op_sel_hi:[1,0]
	v_pk_mul_f32 v[52:53], v[36:37], v[52:53]
	v_pk_mul_f32 v[54:55], v[38:39], v[54:55]
	global_store_dwordx4 v6, v[52:55], s[18:19] offset:3072
	s_branch .Lfn_loop
.Lfn_a0_last:
	s_waitcnt vmcnt(0)
	v_fmamk_f32 v20, v20, 0x3a800000, v1
	v_mul_f32_e32 v21, 0x4b800000, v20
	v_cmp_gt_f32_e32 vcc, s1, v20
	s_nop 1
	v_cndmask_b32_e32 v20, v20, v21, vcc
	v_rsq_f32_e32 v20, v20
	s_nop 0
	v_mul_f32_e32 v21, 0x45800000, v20
	v_cndmask_b32_e32 v20, v20, v21, vcc
	v_pk_mul_f32 v[40:41], v[40:41], v[20:21] op_sel_hi:[1,0]
	v_pk_mul_f32 v[42:43], v[42:43], v[20:21] op_sel_hi:[1,0]
	v_pk_mul_f32 v[40:41], v[24:25], v[40:41]
	v_pk_mul_f32 v[42:43], v[26:27], v[42:43]
	global_store_dwordx4 v6, v[40:43], s[18:19] offset:0
	v_pk_mul_f32 v[44:45], v[44:45], v[20:21] op_sel_hi:[1,0]
	v_pk_mul_f32 v[46:47], v[46:47], v[20:21] op_sel_hi:[1,0]
	v_pk_mul_f32 v[44:45], v[28:29], v[44:45]
	v_pk_mul_f32 v[46:47], v[30:31], v[46:47]
	global_store_dwordx4 v6, v[44:47], s[18:19] offset:1024
	v_pk_mul_f32 v[48:49], v[48:49], v[20:21] op_sel_hi:[1,0]
	v_pk_mul_f32 v[50:51], v[50:51], v[20:21] op_sel_hi:[1,0]
	v_pk_mul_f32 v[48:49], v[32:33], v[48:49]
	v_pk_mul_f32 v[50:51], v[34:35], v[50:51]
	global_store_dwordx4 v6, v[48:51], s[18:19] offset:2048
	v_pk_mul_f32 v[52:53], v[52:53], v[20:21] op_sel_hi:[1,0]
	v_pk_mul_f32 v[54:55], v[54:55], v[20:21] op_sel_hi:[1,0]
	v_pk_mul_f32 v[52:53], v[36:37], v[52:53]
	v_pk_mul_f32 v[54:55], v[38:39], v[54:55]
	global_store_dwordx4 v6, v[52:55], s[18:19] offset:3072
	s_branch .LBB0_2410
.Lfn_b_last:
	s_waitcnt vmcnt(0)
	v_fmamk_f32 v22, v22, 0x3a800000, v1
	v_mul_f32_e32 v23, 0x4b800000, v22
	v_cmp_gt_f32_e32 vcc, s1, v22
	s_nop 1
	v_cndmask_b32_e32 v22, v22, v23, vcc
	v_rsq_f32_e32 v22, v22
	s_nop 0
	v_mul_f32_e32 v23, 0x45800000, v22
	v_cndmask_b32_e32 v22, v22, v23, vcc
	v_pk_mul_f32 v[56:57], v[56:57], v[22:23] op_sel_hi:[1,0]
	v_pk_mul_f32 v[58:59], v[58:59], v[22:23] op_sel_hi:[1,0]
	v_pk_mul_f32 v[56:57], v[24:25], v[56:57]
	v_pk_mul_f32 v[58:59], v[26:27], v[58:59]
	global_store_dwordx4 v6, v[56:59], s[18:19] offset:0
	v_pk_mul_f32 v[60:61], v[60:61], v[22:23] op_sel_hi:[1,0]
	v_pk_mul_f32 v[62:63], v[62:63], v[22:23] op_sel_hi:[1,0]
	v_pk_mul_f32 v[60:61], v[28:29], v[60:61]
	v_pk_mul_f32 v[62:63], v[30:31], v[62:63]
	global_store_dwordx4 v6, v[60:63], s[18:19] offset:1024
	v_pk_mul_f32 v[64:65], v[64:65], v[22:23] op_sel_hi:[1,0]
	v_pk_mul_f32 v[66:67], v[66:67], v[22:23] op_sel_hi:[1,0]
	v_pk_mul_f32 v[64:65], v[32:33], v[64:65]
	v_pk_mul_f32 v[66:67], v[34:35], v[66:67]
	global_store_dwordx4 v6, v[64:67], s[18:19] offset:2048
	v_pk_mul_f32 v[68:69], v[68:69], v[22:23] op_sel_hi:[1,0]
	v_pk_mul_f32 v[70:71], v[70:71], v[22:23] op_sel_hi:[1,0]
	v_pk_mul_f32 v[68:69], v[36:37], v[68:69]
	v_pk_mul_f32 v[70:71], v[38:39], v[70:71]
	global_store_dwordx4 v6, v[68:71], s[18:19] offset:3072
	s_branch .LBB0_2410
